# v14 plus next-tile touch prefetch also in the padded w_in convert tiles
# speedup vs baseline: 1.0222x; 1.0002x over previous
; DEVI int srccol_ffn(int n) { return ((n >> 7) & 1) * FFN_H + (n >> 8) * 128 + (n & 127); }
; DEVI void conv_tile(unsigned char* smem, const float* src, int ldsrc, int K, bf16_t* dst, int mode, int ntile, int ktile) {
;     ...
;     const int n = n0 + tx;
;     const int sc = mode == 0 ? srccol_win(n) : (mode == 1 ? srccol_ffn(n) : n);
; #pragma unroll
;     for (int i = 0; i < 8; ++i) {
;         const int kk = ty + 8 * i;
;         tile[kk * 65 + tx] = sc >= 0 ? src[(size_t)(k0 + kk) * ldsrc + sc] : 0.0f;
;     }
.LBB0_37:
	s_or_b64 exec, exec, s[4:5]
	s_and_saveexec_b64 s[4:5], vcc
	s_add_i32 s101, s18, s90
	s_cmp_lt_u32 s101, 0x1d80
	s_cbranch_scc0 .Lcvt_nt_winA
	global_load_dword v244, v[228:229], off offset:2048
	global_load_dword v244, v[230:231], off offset:2048
	global_load_dword v244, v[232:233], off offset:2048
	global_load_dword v244, v[234:235], off offset:2048
	global_load_dword v244, v[236:237], off offset:2048
	global_load_dword v244, v[238:239], off offset:2048
	global_load_dword v244, v[240:241], off offset:2048
	global_load_dword v244, v[242:243], off offset:2048
	s_branch .Lcvt_j_winA

; DEVI void conv_tile(unsigned char* smem, const float* src, int ldsrc, int K, bf16_t* dst, int mode, int ntile, int ktile) {
;     ...
;         tile[kk * 65 + tx] = sc >= 0 ? src[(size_t)(k0 + kk) * ldsrc + sc] : 0.0f;
;     }
;     __syncthreads();
;     const int nr = tid >> 3, ks = (tid & 7) * 8;
;     float v[8];
; #pragma unroll
;     for (int j = 0; j < 8; ++j) v[j] = tile[(ks + j) * 65 + nr];
;     u32x4 w; w.x = cvt_pk_bf16(v[0], v[1]); w.y = cvt_pk_bf16(v[2], v[3]); w.z = cvt_pk_bf16(v[4], v[5]); w.w = cvt_pk_bf16(v[6], v[7]);
;     *(u32x4*)(dst + (size_t)(n0 + nr) * K + k0 + ks) = w;
;     __syncthreads();
.Lcvt_j_winA:
	s_or_b64 exec, exec, s[4:5]
	s_waitcnt vmcnt(8)
	ds_write_b32 v2, v220
	ds_write_b32 v2, v221 offset:2080
	ds_write_b32 v2, v222 offset:4160
	ds_write_b32 v2, v223 offset:6240
	ds_write_b32 v2, v224 offset:8320
	ds_write_b32 v2, v225 offset:10400
	ds_write_b32 v2, v226 offset:12480
	ds_write_b32 v2, v227 offset:14560
	v_ashrrev_i32_e32 v2, 3, v1
	v_lshlrev_b32_e32 v1, 3, v1
	v_and_b32_e32 v1, 56, v1
	v_lshlrev_b32_e32 v4, 2, v2
	v_mul_u32_u24_e32 v5, 0x104, v1
	v_add3_u32 v8, 0, v4, v5
	s_waitcnt lgkmcnt(0)
	s_barrier
	ds_read2_b32 v[4:5], v8 offset1:65
	ds_read2_b32 v[6:7], v8 offset0:130 offset1:195
	v_add_u32_e32 v10, 0x400, v8
	ds_read2_b32 v[8:9], v10 offset0:4 offset1:69
	ds_read2_b32 v[10:11], v10 offset0:134 offset1:199
	s_lshl_b32 s2, s2, 11
	s_waitcnt lgkmcnt(3)
	v_cvt_pk_bf16_f32 v4, v4, v5
	s_waitcnt lgkmcnt(2)
	v_cvt_pk_bf16_f32 v5, v6, v7
	s_waitcnt lgkmcnt(1)
	v_cvt_pk_bf16_f32 v6, v8, v9
	v_add_u32_e32 v8, s0, v2
	v_ashrrev_i32_e32 v9, 31, v8
	s_sub_i32 s4, s3, s2
	v_lshlrev_b64 v[8:9], 12, v[8:9]
	v_lshl_add_u64 v[8:9], s[88:89], 0, v[8:9]
	s_ashr_i32 s5, s4, 31
	v_lshl_add_u64 v[8:9], s[4:5], 1, v[8:9]
	v_lshlrev_b32_e32 v2, 1, v1
	s_waitcnt lgkmcnt(0)
	v_cvt_pk_bf16_f32 v7, v10, v11
	v_lshl_add_u64 v[8:9], v[8:9], 0, v[2:3]
	global_store_dwordx4 v[8:9], v[4:7], off
	s_barrier

; DEVI int srccol_ffn(int n) { return ((n >> 7) & 1) * FFN_H + (n >> 8) * 128 + (n & 127); }
; DEVI void conv_tile(unsigned char* smem, const float* src, int ldsrc, int K, bf16_t* dst, int mode, int ntile, int ktile) {
;     ...
;     const int n = n0 + tx;
;     const int sc = mode == 0 ? srccol_win(n) : (mode == 1 ? srccol_ffn(n) : n);
; #pragma unroll
;     for (int i = 0; i < 8; ++i) {
;         const int kk = ty + 8 * i;
;         tile[kk * 65 + tx] = sc >= 0 ? src[(size_t)(k0 + kk) * ldsrc + sc] : 0.0f;
;     }
.LBB0_80:
	s_or_b64 exec, exec, s[4:5]
	v_readlane_b32 s36, v252, 6
	v_readlane_b32 s48, v252, 18
	v_readlane_b32 s49, v252, 19
	v_ashrrev_i32_e32 v6, 6, v1
	v_cmp_lt_i32_e32 vcc, -1, v2
	v_lshl_add_u64 v[4:5], v[2:3], 2, s[48:49]
	v_mov_b32_e32 v8, 0
	v_mov_b32_e32 v9, 0
	v_readlane_b32 s37, v252, 7
	v_readlane_b32 s38, v252, 8
	v_readlane_b32 s39, v252, 9
	v_readlane_b32 s40, v252, 10
	v_readlane_b32 s41, v252, 11
	v_readlane_b32 s42, v252, 12
	v_readlane_b32 s43, v252, 13
	v_readlane_b32 s44, v252, 14
	v_readlane_b32 s45, v252, 15
	v_readlane_b32 s46, v252, 16
	v_readlane_b32 s47, v252, 17
	v_readlane_b32 s50, v252, 20
	v_readlane_b32 s51, v252, 21
	v_mov_b32_e32 v220, 0
	s_and_saveexec_b64 s[4:5], vcc
	s_cbranch_execz .LBB0_82
	s_lshl_b32 s6, s2, 11
	v_subrev_u32_e32 v2, s6, v6
	v_add_u32_e32 v2, s3, v2
	v_mad_i64_i32 v[10:11], s[6:7], v2, s17, v[4:5]
	global_load_dword v220, v[10:11], off
	v_mov_b64_e32 v[228:229], v[10:11]
.LBB0_82:
	s_or_b64 exec, exec, s[4:5]
	v_lshl_add_u32 v2, v7, 2, 0
	v_mul_lo_u32 v7, v6, s15
	v_add_u32_e32 v2, v2, v7
	v_mov_b32_e32 v221, 0
	s_and_saveexec_b64 s[4:5], vcc
	s_cbranch_execz .LBB0_84
	s_lshl_b32 s6, s2, 11
	v_subrev_u32_e32 v7, s6, v6
	v_add3_u32 v7, s3, v7, 8
	v_mad_i64_i32 v[8:9], s[6:7], v7, s17, v[4:5]
	global_load_dword v221, v[8:9], off
	v_mov_b64_e32 v[230:231], v[8:9]
.LBB0_84:
	s_or_b64 exec, exec, s[4:5]
	v_mov_b32_e32 v7, 0
	v_mov_b32_e32 v8, 0
	v_mov_b32_e32 v222, 0
	s_and_saveexec_b64 s[4:5], vcc
	s_cbranch_execz .LBB0_86
	s_lshl_b32 s6, s2, 11
	v_subrev_u32_e32 v8, s6, v6
	v_add3_u32 v8, s3, v8, 16
	v_mad_i64_i32 v[8:9], s[6:7], v8, s17, v[4:5]
	global_load_dword v222, v[8:9], off
	v_mov_b64_e32 v[232:233], v[8:9]
.LBB0_86:
	s_or_b64 exec, exec, s[4:5]
	v_mov_b32_e32 v223, 0
	s_and_saveexec_b64 s[4:5], vcc
	s_cbranch_execz .LBB0_88
	s_lshl_b32 s6, s2, 11
	v_subrev_u32_e32 v7, s6, v6
	v_add3_u32 v7, s3, v7, 24
	v_mad_i64_i32 v[8:9], s[6:7], v7, s17, v[4:5]
	global_load_dword v223, v[8:9], off
	v_mov_b64_e32 v[234:235], v[8:9]
.LBB0_88:
	s_or_b64 exec, exec, s[4:5]
	v_mov_b32_e32 v7, 0
	v_mov_b32_e32 v8, 0
	v_mov_b32_e32 v224, 0
	s_and_saveexec_b64 s[4:5], vcc
	s_cbranch_execz .LBB0_90
	s_lshl_b32 s6, s2, 11
	v_subrev_u32_e32 v8, s6, v6
	v_add3_u32 v8, s3, v8, 32
	v_mad_i64_i32 v[8:9], s[6:7], v8, s17, v[4:5]
	global_load_dword v224, v[8:9], off
	v_mov_b64_e32 v[236:237], v[8:9]
.LBB0_90:
	s_or_b64 exec, exec, s[4:5]
	v_mov_b32_e32 v225, 0
	s_and_saveexec_b64 s[4:5], vcc
	s_cbranch_execz .LBB0_92
	s_lshl_b32 s6, s2, 11
	v_subrev_u32_e32 v7, s6, v6
	v_add3_u32 v7, s3, v7, 40
	v_mad_i64_i32 v[8:9], s[6:7], v7, s17, v[4:5]
	global_load_dword v225, v[8:9], off
	v_mov_b64_e32 v[238:239], v[8:9]
.LBB0_92:
	s_or_b64 exec, exec, s[4:5]
	v_mov_b32_e32 v7, 0
	v_mov_b32_e32 v8, 0
	v_mov_b32_e32 v226, 0
	s_and_saveexec_b64 s[4:5], vcc
	s_cbranch_execz .LBB0_94
	s_lshl_b32 s6, s2, 11
	v_subrev_u32_e32 v8, s6, v6
	v_add3_u32 v8, s3, v8, 48
	v_mad_i64_i32 v[8:9], s[6:7], v8, s17, v[4:5]
	global_load_dword v226, v[8:9], off
	v_mov_b64_e32 v[240:241], v[8:9]
.LBB0_94:
	s_or_b64 exec, exec, s[4:5]
	v_mov_b32_e32 v227, 0
	s_and_saveexec_b64 s[4:5], vcc
	s_cbranch_execz .LBB0_37
	s_lshl_b32 s6, s2, 11
	v_subrev_u32_e32 v6, s6, v6
	v_add3_u32 v6, s3, v6, 56
	v_mad_i64_i32 v[4:5], s[6:7], v6, s17, v[4:5]
	global_load_dword v227, v[4:5], off
	v_mov_b64_e32 v[242:243], v[4:5]
	s_branch .LBB0_37

; DEVI int srccol_ffn(int n) { return ((n >> 7) & 1) * FFN_H + (n >> 8) * 128 + (n & 127); }
; DEVI void conv_tile(unsigned char* smem, const float* src, int ldsrc, int K, bf16_t* dst, int mode, int ntile, int ktile) {
;     ...
;     const int n = n0 + tx;
;     const int sc = mode == 0 ? srccol_win(n) : (mode == 1 ? srccol_ffn(n) : n);
; #pragma unroll
;     for (int i = 0; i < 8; ++i) {
;         const int kk = ty + 8 * i;
;         tile[kk * 65 + tx] = sc >= 0 ? src[(size_t)(k0 + kk) * ldsrc + sc] : 0.0f;
;     }
.LBB0_134:
	s_or_b64 exec, exec, s[0:1]
	s_and_saveexec_b64 s[0:1], vcc
	s_add_i32 s101, s15, s90
	s_cmp_lt_u32 s101, 0x1d80
	s_cbranch_scc0 .Lcvt_nt_winB
	global_load_dword v244, v[228:229], off offset:2048
	global_load_dword v244, v[230:231], off offset:2048
	global_load_dword v244, v[232:233], off offset:2048
	global_load_dword v244, v[234:235], off offset:2048
	global_load_dword v244, v[236:237], off offset:2048
	global_load_dword v244, v[238:239], off offset:2048
	global_load_dword v244, v[240:241], off offset:2048
	global_load_dword v244, v[242:243], off offset:2048
	s_branch .Lcvt_j_winB

; DEVI void conv_tile(unsigned char* smem, const float* src, int ldsrc, int K, bf16_t* dst, int mode, int ntile, int ktile) {
;     ...
;         tile[kk * 65 + tx] = sc >= 0 ? src[(size_t)(k0 + kk) * ldsrc + sc] : 0.0f;
;     }
;     __syncthreads();
;     const int nr = tid >> 3, ks = (tid & 7) * 8;
;     float v[8];
; #pragma unroll
;     for (int j = 0; j < 8; ++j) v[j] = tile[(ks + j) * 65 + nr];
;     u32x4 w; w.x = cvt_pk_bf16(v[0], v[1]); w.y = cvt_pk_bf16(v[2], v[3]); w.z = cvt_pk_bf16(v[4], v[5]); w.w = cvt_pk_bf16(v[6], v[7]);
;     *(u32x4*)(dst + (size_t)(n0 + nr) * K + k0 + ks) = w;
;     __syncthreads();
.Lcvt_j_winB:
	s_or_b64 exec, exec, s[0:1]
	v_lshlrev_b32_e32 v0, 3, v2
	v_ashrrev_i32_e32 v8, 3, v2
	v_and_b32_e32 v9, 56, v0
	v_lshlrev_b32_e32 v0, 2, v8
	v_mul_u32_u24_e32 v1, 0x104, v9
	s_waitcnt vmcnt(8)
	ds_write_b32 v4, v220
	ds_write_b32 v4, v221 offset:2080
	ds_write_b32 v4, v222 offset:4160
	ds_write_b32 v4, v223 offset:6240
	ds_write_b32 v4, v224 offset:8320
	ds_write_b32 v4, v225 offset:10400
	ds_write_b32 v4, v226 offset:12480
	ds_write_b32 v4, v227 offset:14560
	v_add3_u32 v4, 0, v0, v1
	s_waitcnt lgkmcnt(0)
	s_barrier
	ds_read2_b32 v[0:1], v4 offset1:65
	ds_read2_b32 v[2:3], v4 offset0:130 offset1:195
	v_add_u32_e32 v6, 0x400, v4
	ds_read2_b32 v[4:5], v6 offset0:4 offset1:69
	ds_read2_b32 v[6:7], v6 offset0:134 offset1:199
	s_lshl_b32 s0, s3, 11
	s_waitcnt lgkmcnt(3)
	v_cvt_pk_bf16_f32 v0, v0, v1
	s_waitcnt lgkmcnt(2)
	v_cvt_pk_bf16_f32 v1, v2, v3
	s_waitcnt lgkmcnt(1)
	v_cvt_pk_bf16_f32 v2, v4, v5
	v_add_u32_e32 v4, s2, v8
	v_ashrrev_i32_e32 v5, 31, v4
	s_sub_i32 s0, s14, s0
	v_lshlrev_b64 v[4:5], 12, v[4:5]
	v_lshl_add_u64 v[4:5], s[88:89], 0, v[4:5]
	s_ashr_i32 s1, s0, 31
	v_lshl_add_u64 v[4:5], s[0:1], 1, v[4:5]
	v_lshlrev_b32_e32 v148, 1, v9
	s_waitcnt lgkmcnt(0)
	v_cvt_pk_bf16_f32 v3, v6, v7
	v_lshl_add_u64 v[4:5], v[4:5], 0, v[148:149]
	global_store_dwordx4 v[4:5], v[0:3], off
	s_barrier

; DEVI int srccol_ffn(int n) { return ((n >> 7) & 1) * FFN_H + (n >> 8) * 128 + (n & 127); }
; DEVI void conv_tile(unsigned char* smem, const float* src, int ldsrc, int K, bf16_t* dst, int mode, int ntile, int ktile) {
;     ...
;     const int n = n0 + tx;
;     const int sc = mode == 0 ? srccol_win(n) : (mode == 1 ? srccol_ffn(n) : n);
; #pragma unroll
;     for (int i = 0; i < 8; ++i) {
;         const int kk = ty + 8 * i;
;         tile[kk * 65 + tx] = sc >= 0 ? src[(size_t)(k0 + kk) * ldsrc + sc] : 0.0f;
;     }
.LBB0_177:
	s_or_b64 exec, exec, s[0:1]
	v_readlane_b32 s0, v254, 10
	v_readlane_b32 s1, v254, 11
	v_ashrrev_i32_e32 v3, 6, v2
	v_cmp_lt_i32_e32 vcc, -1, v148
	v_lshl_add_u64 v[0:1], v[148:149], 2, s[0:1]
	v_mov_b32_e32 v5, 0
	v_mov_b32_e32 v6, 0
	v_mov_b32_e32 v220, 0
	s_and_saveexec_b64 s[0:1], vcc
	s_cbranch_execz .LBB0_179
	s_lshl_b32 s6, s3, 11
	v_subrev_u32_e32 v6, s6, v3
	v_add_u32_e32 v6, s14, v6
	s_mov_b32 s6, 0xf340
	v_mad_i64_i32 v[6:7], s[6:7], v6, s6, v[0:1]
	global_load_dword v220, v[6:7], off
	v_mov_b64_e32 v[228:229], v[6:7]
.LBB0_179:
	s_or_b64 exec, exec, s[0:1]
	v_lshl_add_u32 v4, v4, 2, 0
	v_mul_lo_u32 v7, v3, s86
	v_add_u32_e32 v4, v4, v7
	v_mov_b32_e32 v221, 0
	s_and_saveexec_b64 s[0:1], vcc
	s_cbranch_execz .LBB0_181
	s_lshl_b32 s6, s3, 11
	v_subrev_u32_e32 v5, s6, v3
	v_add3_u32 v5, s14, v5, 8
	s_mov_b32 s6, 0xf340
	v_mad_i64_i32 v[6:7], s[6:7], v5, s6, v[0:1]
	global_load_dword v221, v[6:7], off
	v_mov_b64_e32 v[230:231], v[6:7]
.LBB0_181:
	s_or_b64 exec, exec, s[0:1]
	v_mov_b32_e32 v5, 0
	v_mov_b32_e32 v6, 0
	v_mov_b32_e32 v222, 0
	s_and_saveexec_b64 s[0:1], vcc
	s_cbranch_execz .LBB0_183
	s_lshl_b32 s6, s3, 11
	v_subrev_u32_e32 v6, s6, v3
	v_add3_u32 v6, s14, v6, 16
	s_mov_b32 s6, 0xf340
	v_mad_i64_i32 v[6:7], s[6:7], v6, s6, v[0:1]
	global_load_dword v222, v[6:7], off
	v_mov_b64_e32 v[232:233], v[6:7]
.LBB0_183:
	s_or_b64 exec, exec, s[0:1]
	v_mov_b32_e32 v223, 0
	s_and_saveexec_b64 s[0:1], vcc
	s_cbranch_execz .LBB0_185
	s_lshl_b32 s6, s3, 11
	v_subrev_u32_e32 v5, s6, v3
	v_add3_u32 v5, s14, v5, 24
	s_mov_b32 s6, 0xf340
	v_mad_i64_i32 v[6:7], s[6:7], v5, s6, v[0:1]
	global_load_dword v223, v[6:7], off
	v_mov_b64_e32 v[234:235], v[6:7]
.LBB0_185:
	s_or_b64 exec, exec, s[0:1]
	v_mov_b32_e32 v5, 0
	v_mov_b32_e32 v6, 0
	v_mov_b32_e32 v224, 0
	s_and_saveexec_b64 s[0:1], vcc
	s_cbranch_execz .LBB0_187
	s_lshl_b32 s6, s3, 11
	v_subrev_u32_e32 v6, s6, v3
	v_add3_u32 v6, s14, v6, 32
	s_mov_b32 s6, 0xf340
	v_mad_i64_i32 v[6:7], s[6:7], v6, s6, v[0:1]
	global_load_dword v224, v[6:7], off
	v_mov_b64_e32 v[236:237], v[6:7]
.LBB0_187:
	s_or_b64 exec, exec, s[0:1]
	v_mov_b32_e32 v225, 0
	s_and_saveexec_b64 s[0:1], vcc
	s_cbranch_execz .LBB0_189
	s_lshl_b32 s6, s3, 11
	v_subrev_u32_e32 v5, s6, v3
	v_add3_u32 v5, s14, v5, 40
	s_mov_b32 s6, 0xf340
	v_mad_i64_i32 v[6:7], s[6:7], v5, s6, v[0:1]
	global_load_dword v225, v[6:7], off
	v_mov_b64_e32 v[238:239], v[6:7]
.LBB0_189:
	s_or_b64 exec, exec, s[0:1]
	v_mov_b32_e32 v5, 0
	v_mov_b32_e32 v6, 0
	v_mov_b32_e32 v226, 0
	s_and_saveexec_b64 s[0:1], vcc
	s_cbranch_execz .LBB0_191
	s_lshl_b32 s6, s3, 11
	v_subrev_u32_e32 v6, s6, v3
	v_add3_u32 v6, s14, v6, 48
	s_mov_b32 s6, 0xf340
	v_mad_i64_i32 v[6:7], s[6:7], v6, s6, v[0:1]
	global_load_dword v226, v[6:7], off
	v_mov_b64_e32 v[240:241], v[6:7]
.LBB0_191:
	s_or_b64 exec, exec, s[0:1]
	v_mov_b32_e32 v227, 0
	s_and_saveexec_b64 s[0:1], vcc
	s_cbranch_execz .LBB0_134
	s_lshl_b32 s6, s3, 11
	v_subrev_u32_e32 v3, s6, v3
	v_add3_u32 v3, s14, v3, 56
	s_mov_b32 s6, 0xf340
	v_mad_i64_i32 v[0:1], s[6:7], v3, s6, v[0:1]
	global_load_dword v227, v[0:1], off
	v_mov_b64_e32 v[242:243], v[0:1]
	s_branch .LBB0_134
